# v18: mLSTM chunk head - per-chunk (max, decay) LDS record read one chunk ahead (no exposed LDS wait at chunk start), on top of v17
# baseline (speedup 1.0000x reference)
; #define LAS __attribute__((address_space(3)))
; #define gpart ((float*)S7(IPRE_OFF))
; template <int SKIP>
; DEV void mlstm_phase(LAS char* shm, const bf16_t* q, const bf16_t* k, const bf16_t* v, const float* gpart, const float* b_ig, const float* b_fg, bf16_t* hc, const bool pre) {
;     ...
;         const int vs = (item >> 3) & 7, bh = (item & 7) + 8 * (item >> 6), h = bh & 3, b = bh >> 2;
;         const size_t cb0 = ((size_t)(b * SEQ)) * DM + h * DH;
;         __syncthreads();
;         unsigned kvoff; { const int rw = 2 * wid + (lane >> 5); kvoff = (unsigned)(rw * DM + (((lane & 31) ^ rw) * 8)) * 2u; asm volatile("" : "+v"(kvoff)); }
;     ...
;         MLK_ISSUE(cb0, 0);
;         bf16x8 qfr[8];
;         const bf16_t* qfb = q + ((size_t)((b * 4 + h) * 32) * 4 + (wid & 3)) * 4096 + lane * 8;
; #pragma unroll
;         for (int ks = 0; ks < 8; ++ks) qfr[ks] = *(const bf16x8*)(qfb + ks * 512);
;         uint4 vv = make_uint4(0, 0, 0, 0);
;         if (wid < 4) vv = *(const uint4*)(v + cb0 + (size_t)(tid >> 2) * DM + vs * 32 + (tid & 3) * 8);
;         for (int i = tid; i < (CB + 25344 - VT) / 4; i += 512) ((LAS unsigned*)(shm + VT))[i] = 0u;
;         if (!(pre && item == (int)blockIdx.x)) mlstm_gate_scans(shm, gpart, b_ig, b_fg, item);
;         __syncthreads();
;         if (wid == 0) *(LAS unsigned*)(shm + VT + tid * VRS + 64) = 0x3F80u;
;         const int ndt = (wid == 0 || wid == 4 || wid == 1) ? 3 : ((wid == 5 || wid == 2) ? 2 : 1);
;         const int dt0 = (wid == 0) ? 0 : (wid == 4) ? 3 : (wid == 1) ? 6 : (wid == 5) ? 9 : (wid == 2) ? 11 : (wid == 6) ? 13 : (wid == 3) ? 14 : 15;
;         f32x4 cacc[3][3];
; #pragma unroll
;         for (int i = 0; i < 3; ++i)
; #pragma unroll
;             for (int vt = 0; vt < 3; ++vt) cacc[i][vt] = (f32x4){0.f, 0.f, 0.f, 0.f};
;         float m_prev = 0.f;
; #pragma nounroll
;         for (int j = 0; j < SEQ / CHUNK; ++j) {
;             const size_t cb = cb0 + (size_t)j * CHUNK * DM;
;             const float btot = __int_as_float(__builtin_amdgcn_readfirstlane(__float_as_int(tc[2 * j]))), amax = __int_as_float(__builtin_amdgcn_readfirstlane(__float_as_int(tc[2 * j + 1])));
.LBB0_634:
	s_bfe_u32 s0, s79, 0x10002
	s_lshl_b32 s1, s0, 11
	s_lshl_b32 s40, s0, 2
	s_and_b32 s0, s57, 7
	s_lshl_b32 s41, s0, 6
	s_lshl_b32 s0, s38, 1
	s_and_b32 s39, s78, 3
	v_bitop3_b32 v0, s0, v189, v188 bitop3:0x36
	s_lshl_b32 s74, s39, 9
	v_lshlrev_b32_e32 v167, 4, v0
	v_bitop3_b32 v0, s0, v191, v188 bitop3:0x36
	v_lshlrev_b32_e32 v220, 4, v0
	s_cmp_gt_u32 s36, 1
	v_add_u32_e32 v0, s0, v196
	s_cselect_b64 s[34:35], -1, 0
	v_xor_b32_e32 v1, v0, v189
	v_xor_b32_e32 v0, v0, v191
	s_cmp_eq_u32 s36, 3
	v_lshlrev_b32_e32 v222, 4, v0
	s_cselect_b64 s[36:37], -1, 0
	v_add_u32_e32 v0, s0, v197
	s_lshl_b32 s0, s45, 9
	s_and_b32 s0, s0, 0xfffff000
	s_or_b32 s0, s0, s1
	s_ashr_i32 s1, s0, 31
	s_lshl_b64 s[28:29], s[0:1], 11
	s_add_u32 s30, s55, s28
	s_addc_u32 s31, s56, s29
	v_lshl_add_u64 v[168:169], s[30:31], 0, v[2:3]
	s_add_i32 s30, s52, s40
	v_lshlrev_b32_e32 v221, 4, v1
	v_xor_b32_e32 v1, v0, v189
	v_xor_b32_e32 v0, v0, v191
	s_add_i32 s30, s30, s39
	v_lshlrev_b32_e32 v223, 4, v1
	v_lshlrev_b32_e32 v224, 4, v0
	s_lshl_b32 s30, s30, 5
	v_lshl_add_u64 v[0:1], v[158:159], 0, s[0:1]
	v_lshl_add_u32 v54, s38, 5, v192
	s_ashr_i32 s31, s30, 31
	v_lshlrev_b64 v[0:1], 11, v[0:1]
	v_mov_b32_e32 v4, v3
	v_mov_b32_e32 v5, v3
	s_lshl_b64 s[30:31], s[30:31], 15
	s_or_b32 s28, s28, s41
	v_or_b32_e32 v0, s41, v0
	v_mov_b32_e32 v2, v3
	v_add_u32_e32 v225, v54, v178
	v_add_u32_e32 v226, v54, v195
	v_mov_b64_e32 v[64:65], v[4:5]
	v_mov_b64_e32 v[68:69], v[4:5]
	v_mov_b64_e32 v[56:57], v[4:5]
	v_mov_b64_e32 v[72:73], v[4:5]
	v_mov_b64_e32 v[76:77], v[4:5]
	v_mov_b64_e32 v[60:61], v[4:5]
	v_lshl_add_u64 v[170:171], v[154:155], 0, s[30:31]
	v_lshl_add_u64 v[172:173], v[162:163], 0, s[28:29]
	v_lshl_add_u64 v[174:175], v[164:165], 0, v[0:1]
	s_mov_b32 s28, 0
	s_movk_i32 s40, 0xe000
	s_mov_b64 s[38:39], 0
	v_mov_b32_e32 v42, 0
	v_mov_b32_e32 v43, 0
	v_mov_b32_e32 v44, 0
	v_mov_b32_e32 v45, 0
	v_mov_b32_e32 v46, 0
	v_mov_b32_e32 v47, 0
	v_mov_b32_e32 v48, 0
	v_mov_b32_e32 v49, 0
	v_mov_b32_e32 v50, 0
	v_mov_b32_e32 v51, 0
	v_mov_b32_e32 v52, 0
	v_mov_b32_e32 v53, 0
	s_mov_b32 s41, s54
	v_mov_b64_e32 v[62:63], v[2:3]
	v_mov_b64_e32 v[66:67], v[2:3]
	v_mov_b64_e32 v[54:55], v[2:3]
	v_mov_b64_e32 v[70:71], v[2:3]
	v_mov_b64_e32 v[74:75], v[2:3]
	v_mov_b64_e32 v[58:59], v[2:3]
	s_add_i32 s0, s41, -4
	v_mov_b32_e32 v0, s0
	ds_read_b32 v239, v0
	ds_read_b32 v241, v0 offset:4
	s_waitcnt lgkmcnt(0)
	s_branch .LBB0_636

; template <int SKIP>
; DEV void mlstm_phase(LAS char* shm, const bf16_t* q, const bf16_t* k, const bf16_t* v, const float* gpart, const float* b_ig, const float* b_fg, bf16_t* hc, const bool pre) {
;     ...
;         for (int j = 0; j < SEQ / CHUNK; ++j) {
;             const size_t cb = cb0 + (size_t)j * CHUNK * DM;
;             const float btot = __int_as_float(__builtin_amdgcn_readfirstlane(__float_as_int(tc[2 * j]))), amax = __int_as_float(__builtin_amdgcn_readfirstlane(__float_as_int(tc[2 * j + 1])));
;             const float mxc = __int_as_float(__builtin_amdgcn_readfirstlane(__float_as_int(fmaxf(m_prev, amax))));
.LBB0_636:
	s_add_i32 s0, s41, 4
	v_mov_b32_e32 v0, s0
	v_max_f32_e64 v227, s28, s28
	s_mov_b64 s[0:1], -1
	s_and_b64 vcc, exec, s[84:85]
	v_readfirstlane_b32 s29, v241
	v_readfirstlane_b32 s42, v239
	ds_read_b32 v239, v0
	ds_read_b32 v241, v0 offset:4
	v_max_f32_e64 v0, s29, s29
	v_max_f32_e32 v0, v227, v0
	s_nop 0
	v_readfirstlane_b32 s43, v0
	s_cbranch_vccnz .LBB0_643
	s_andn2_b64 vcc, exec, s[0:1]
	s_cbranch_vccz .LBB0_644

; #define LAS __attribute__((address_space(3)))
; template <int TT>
; DEV void mlstm_a_wave(LAS char* shm, const LAS char* kbuf, const bf16x8 (&qfr)[8], int fr, int fq, float m_prev, const LAS float* tpj, const LAS float* taj, f32x4 (&nacc)[3]) {
;     constexpr int VT = 67584, VRS = 96, NT = TT + 1;
;     const LAS char* kb = kbuf + fr * 512 + ((fq ^ (fr & 3)) << 4);
;     int xo[4];
; #pragma unroll
;     for (int b_ = 0; b_ < 4; ++b_) xo[b_] = ((b_ ^ (fr >> 2)) << 6);
;     ...
;     f32x4 sacc[NT];
; #pragma unroll
;     for (int jj = 0; jj < NT; ++jj) sacc[jj] = (f32x4){0.f, 0.f, 0.f, 0.f};
;     bf16x8 kf[NT];
; #pragma unroll
;     for (int jj = 0; jj < NT; ++jj) kf[jj] = *(const LAS bf16x8*)MLK_ADDR(jj, 0);
; #pragma unroll
;     for (int ks = 0; ks < 8; ++ks) {
;         bf16x8 kn[NT];
; #pragma unroll
;         for (int jj = 0; jj < NT; ++jj) kn[jj] = kf[jj];
;         if (ks < 7) {
; #pragma unroll
;             for (int jj = 0; jj < NT; ++jj) kn[jj] = *(const LAS bf16x8*)MLK_ADDR(jj, ks + 1);
;         }
; #pragma unroll
;         for (int jj = 0; jj < NT; ++jj) sacc[jj] = __builtin_amdgcn_mfma_f32_16x16x32_bf16(kf[jj], qfr[ks], sacc[jj], 0, 0, 0);
; #pragma unroll
;         for (int jj = 0; jj < NT; ++jj) kf[jj] = kn[jj];
;     }
;     ...
;     constexpr int NK = (TT >= 2) ? 2 : 1;
;     s16x4 vlo[NK][3], vhi[NK][3];
; #pragma unroll
;     for (int kk = 0; kk < NK; ++kk)
; #pragma unroll
;         for (int vt = 0; vt < 3; ++vt) {
;             vlo[kk][vt] = __builtin_amdgcn_ds_read_tr16_b64_v4i16((LAS s16x4*)(shm + VT + (32 * kk + 4 * fq + (fr >> 2)) * VRS + (16 * vt + 4 * (fr & 3)) * 2));
;             vhi[kk][vt] = __builtin_amdgcn_ds_read_tr16_b64_v4i16((LAS s16x4*)(shm + VT + (32 * kk + 16 + 4 * fq + (fr >> 2)) * VRS + (16 * vt + 4 * (fr & 3)) * 2));
;         }
;     const int t = 16 * TT + fr;
;     const float btm = -fmaxf(m_prev, tpj[t]);
;     f32x4 sm[2 * NK];
; #pragma unroll
;     for (int jj = 0; jj < 2 * NK; ++jj) {
;         if (jj < NT) {
;             const f32x4 a4 = *(const LAS f32x4*)(taj + 16 * jj + 4 * fq);
.LBB0_652:
	s_and_b32 s29, s38, 0x8000
	s_andn2_b64 vcc, exec, s[0:1]
	s_add_i32 s29, s29, 0
	s_cbranch_vccnz .LBB0_664
	v_add3_u32 v5, s29, v180, v181
	v_add_u32_e32 v4, v5, v182
	ds_read_b128 v[110:113], v4
	s_cmp_lt_i32 s67, 2
	s_mov_b64 s[0:1], -1
	s_cbranch_scc1 .LBB0_659
	s_cmp_gt_i32 s67, 2
	s_cbranch_scc0 .LBB0_656
	v_add_u32_e32 v1, s40, v203
	v_add_u32_e32 v1, 0x235c0, v1
	ds_read_b32 v238, v1
	v_add_u32_e32 v0, s40, v202
	v_add_u32_e32 v1, 0x21580, v0
	ds_read_b128 v[250:253], v1
	v_add_u32_e32 v1, 0x215c0, v0
	ds_read_b128 v[246:249], v1
	ds_read_b128 v[114:117], v4 offset:8192
	ds_read_b128 v[118:121], v4 offset:16384
	ds_read_b128 v[122:125], v4 offset:24576
	v_add_u32_e32 v0, v5, v183
	ds_read_b128 v[126:129], v0
	ds_read_b128 v[130:133], v0 offset:8192
	ds_read_b128 v[134:137], v0 offset:16384
	ds_read_b128 v[138:141], v0 offset:24576
	s_waitcnt lgkmcnt(4)
	v_mfma_f32_16x16x32_bf16 v[142:145], v[110:113], v[38:41], 0
	v_add_u32_e32 v1, v5, v184
	ds_read_b128 v[146:149], v1
	ds_read_b128 v[150:153], v1 offset:8192
	ds_read_b128 v[230:233], v1 offset:16384
	ds_read_b128 v[234:237], v1 offset:24576
	v_add_u32_e32 v229, v5, v185
	v_mfma_f32_16x16x32_bf16 v[114:117], v[114:117], v[38:41], 0
	s_mov_b64 s[0:1], 0
	v_mfma_f32_16x16x32_bf16 v[118:121], v[118:121], v[38:41], 0
	v_mfma_f32_16x16x32_bf16 v[122:125], v[122:125], v[38:41], 0
	s_waitcnt lgkmcnt(4)
	v_mfma_f32_16x16x32_bf16 v[126:129], v[126:129], v[34:37], v[142:145]
	v_mfma_f32_16x16x32_bf16 v[114:117], v[130:133], v[34:37], v[114:117]
	v_mfma_f32_16x16x32_bf16 v[118:121], v[134:137], v[34:37], v[118:121]
	v_mfma_f32_16x16x32_bf16 v[122:125], v[138:141], v[34:37], v[122:125]
	ds_read_b128 v[130:133], v229
	ds_read_b128 v[134:137], v229 offset:8192
	ds_read_b128 v[138:141], v229 offset:16384
	ds_read_b128 v[142:145], v229 offset:24576
	s_waitcnt lgkmcnt(4)
	v_mfma_f32_16x16x32_bf16 v[126:129], v[146:149], v[30:33], v[126:129]
	v_mfma_f32_16x16x32_bf16 v[114:117], v[150:153], v[30:33], v[114:117]
	v_mfma_f32_16x16x32_bf16 v[118:121], v[230:233], v[30:33], v[118:121]
	v_mfma_f32_16x16x32_bf16 v[122:125], v[234:237], v[30:33], v[122:125]
	ds_read_b128 v[146:149], v4 offset:256
	ds_read_b128 v[150:153], v4 offset:8448
	ds_read_b128 v[230:233], v4 offset:16640
	ds_read_b128 v[234:237], v4 offset:24832
	s_waitcnt lgkmcnt(4)
	v_mfma_f32_16x16x32_bf16 v[126:129], v[130:133], v[10:13], v[126:129]
	v_mfma_f32_16x16x32_bf16 v[114:117], v[134:137], v[10:13], v[114:117]
	v_mfma_f32_16x16x32_bf16 v[118:121], v[138:141], v[10:13], v[118:121]
	v_mfma_f32_16x16x32_bf16 v[122:125], v[142:145], v[10:13], v[122:125]
	ds_read_b128 v[130:133], v0 offset:256
	ds_read_b128 v[134:137], v0 offset:8448
	ds_read_b128 v[138:141], v0 offset:16640
	ds_read_b128 v[142:145], v0 offset:24832
	v_add_u32_e32 v0, v187, v186
	s_waitcnt lgkmcnt(4)
	v_mfma_f32_16x16x32_bf16 v[126:129], v[146:149], v[26:29], v[126:129]
	v_mfma_f32_16x16x32_bf16 v[114:117], v[150:153], v[26:29], v[114:117]
	v_mfma_f32_16x16x32_bf16 v[118:121], v[230:233], v[26:29], v[118:121]
	v_mfma_f32_16x16x32_bf16 v[122:125], v[234:237], v[26:29], v[122:125]
	ds_read_b128 v[146:149], v1 offset:256
	ds_read_b128 v[150:153], v1 offset:8448
	ds_read_b128 v[230:233], v1 offset:16640
	ds_read_b128 v[234:237], v1 offset:24832
	s_waitcnt lgkmcnt(4)
	v_mfma_f32_16x16x32_bf16 v[126:129], v[130:133], v[22:25], v[126:129]
	v_mfma_f32_16x16x32_bf16 v[114:117], v[134:137], v[22:25], v[114:117]
	v_mfma_f32_16x16x32_bf16 v[118:121], v[138:141], v[22:25], v[118:121]
	ds_read_b128 v[130:133], v229 offset:256
	ds_read_b128 v[134:137], v229 offset:8448
	ds_read_b128 v[138:141], v229 offset:16640
	ds_read_b128 v[242:245], v229 offset:24832
	v_mfma_f32_16x16x32_bf16 v[122:125], v[142:145], v[22:25], v[122:125]
	s_waitcnt lgkmcnt(4)
	v_mfma_f32_16x16x32_bf16 v[126:129], v[146:149], v[14:17], v[126:129]
	v_mfma_f32_16x16x32_bf16 v[114:117], v[150:153], v[14:17], v[114:117]
	v_mfma_f32_16x16x32_bf16 v[118:121], v[230:233], v[14:17], v[118:121]
	v_mfma_f32_16x16x32_bf16 v[122:125], v[234:237], v[14:17], v[122:125]
	s_waitcnt lgkmcnt(0)
	v_mfma_f32_16x16x32_bf16 v[130:133], v[130:133], v[18:21], v[126:129]
	v_mfma_f32_16x16x32_bf16 v[142:145], v[134:137], v[18:21], v[114:117]
	v_mfma_f32_16x16x32_bf16 v[146:149], v[138:141], v[18:21], v[118:121]
	v_mfma_f32_16x16x32_bf16 v[230:233], v[242:245], v[18:21], v[122:125]
	s_nop 0
	v_add_u32_e32 v5, s40, v202
	v_add_u32_e32 v1, 0x21500, v5
	ds_read_b128 v[150:153], v1
	v_add_u32_e32 v1, 0x21540, v5
	ds_read_b128 v[234:237], v1
	ds_read_b64_tr_b16 v[140:141], v0 offset:1536
	ds_read_b64_tr_b16 v[138:139], v0
	ds_read_b64_tr_b16 v[134:135], v0 offset:32
	ds_read_b64_tr_b16 v[136:137], v0 offset:1568
	ds_read_b64_tr_b16 v[126:127], v0 offset:64
	ds_read_b64_tr_b16 v[128:129], v0 offset:1600
	ds_read_b64_tr_b16 v[118:119], v0 offset:3072
	ds_read_b64_tr_b16 v[120:121], v0 offset:4608
	ds_read_b64_tr_b16 v[114:115], v0 offset:3104
	ds_read_b64_tr_b16 v[116:117], v0 offset:4640
	ds_read_b64_tr_b16 v[122:123], v0 offset:3136
	ds_read_b64_tr_b16 v[124:125], v0 offset:4672
	s_waitcnt lgkmcnt(12)
; DEV unsigned pk2(float lo, float hi) { f32n2 v = {lo, hi}; bf16n2 b = __builtin_convertvector(v, bf16n2); return __builtin_bit_cast(unsigned, b); }
; #define LAS __attribute__((address_space(3)))
; template <int TT>
; DEV void mlstm_a_wave(LAS char* shm, const LAS char* kbuf, const bf16x8 (&qfr)[8], int fr, int fq, float m_prev, const LAS float* tpj, const LAS float* taj, f32x4 (&nacc)[3]) {
;     ...
;     const int t = 16 * TT + fr;
;     const float btm = -fmaxf(m_prev, tpj[t]);
;     f32x4 sm[2 * NK];
; #pragma unroll
;     for (int jj = 0; jj < 2 * NK; ++jj) {
;         if (jj < NT) {
;             const f32x4 a4 = *(const LAS f32x4*)(taj + 16 * jj + 4 * fq);
; #pragma unroll
;             for (int r = 0; r < 4; ++r) {
;                 const int s_ = 16 * jj + 4 * fq + r;
;                 sm[jj][r] = (jj < TT || s_ <= t) ? sacc[jj < NT ? jj : 0][r] * __expf(btm + a4[r]) : 0.f;
;             }
;         } else sm[jj] = (f32x4){0.f, 0.f, 0.f, 0.f};
;     }
; #pragma unroll
;     for (int kk = 0; kk < NK; ++kk) {
;         const u32x4 u = (u32x4){pk2(sm[2 * kk][0], sm[2 * kk][1]), pk2(sm[2 * kk][2], sm[2 * kk][3]), pk2(sm[2 * kk + 1][0], sm[2 * kk + 1][1]), pk2(sm[2 * kk + 1][2], sm[2 * kk + 1][3])};
;         const bf16x8 af = *(const bf16x8*)&u;
; #pragma unroll
;         for (int vt = 0; vt < 3; ++vt) {
;             bf16x8 bv8; bv8[0] = vlo[kk][vt][0]; bv8[1] = vlo[kk][vt][1]; bv8[2] = vlo[kk][vt][2]; bv8[3] = vlo[kk][vt][3];
;             bv8[4] = vhi[kk][vt][0]; bv8[5] = vhi[kk][vt][1]; bv8[6] = vhi[kk][vt][2]; bv8[7] = vhi[kk][vt][3];
;             nacc[vt] = __builtin_amdgcn_mfma_f32_16x16x32_bf16(af, bv8, nacc[vt], 0, 0, 0);
;         }
;     }
	v_max_f32_e32 v0, v238, v238
	v_max_f32_e32 v229, v227, v0
	s_nop 0
	v_sub_f32_e32 v1, v251, v229
	s_nop 0
	v_sub_f32_e32 v0, v246, v229
	v_mul_f32_e32 v0, 0x3fb8aa3b, v0
	v_exp_f32_e32 v0, v0
	v_mul_f32_e32 v1, 0x3fb8aa3b, v1
	v_exp_f32_e32 v1, v1
	v_mul_f32_e32 v0, v230, v0
	v_cndmask_b32_e64 v230, v0, 0, s[6:7]
	v_sub_f32_e32 v0, v247, v229
	v_mul_f32_e32 v0, 0x3fb8aa3b, v0
	v_exp_f32_e32 v0, v0
	s_nop 0
	v_mul_f32_e32 v0, v231, v0
	v_cndmask_b32_e64 v231, 0, v0, s[8:9]
	v_sub_f32_e32 v0, v248, v229
	v_mul_f32_e32 v0, 0x3fb8aa3b, v0
	v_exp_f32_e32 v0, v0
	s_nop 0
	v_mul_f32_e32 v0, v232, v0
	v_cndmask_b32_e64 v232, v0, 0, s[10:11]
	v_sub_f32_e32 v0, v249, v229
	v_mul_f32_e32 v0, 0x3fb8aa3b, v0
	v_exp_f32_e32 v0, v0
	s_nop 0
	v_mul_f32_e32 v0, v233, v0
	v_cndmask_b32_e64 v233, v0, 0, s[12:13]
	v_sub_f32_e32 v0, v250, v229
	v_mul_f32_e32 v0, 0x3fb8aa3b, v0
	v_exp_f32_e32 v0, v0
	s_nop 0
	v_pk_mul_f32 v[0:1], v[146:147], v[0:1]
	v_sub_f32_e32 v146, v252, v229
	v_sub_f32_e32 v147, v253, v229
	v_mul_f32_e32 v146, 0x3fb8aa3b, v146
	v_mul_f32_e32 v147, 0x3fb8aa3b, v147
	v_exp_f32_e32 v146, v146
	v_exp_f32_e32 v147, v147
	s_nop 0
	v_pk_mul_f32 v[146:147], v[148:149], v[146:147]
	v_sub_f32_e32 v148, v234, v229
	v_sub_f32_e32 v149, v235, v229
	v_mul_f32_e32 v148, 0x3fb8aa3b, v148
	v_mul_f32_e32 v149, 0x3fb8aa3b, v149
	v_exp_f32_e32 v148, v148
	v_exp_f32_e32 v149, v149
	s_nop 0
	v_pk_mul_f32 v[142:143], v[142:143], v[148:149]
	v_sub_f32_e32 v148, v236, v229
	v_sub_f32_e32 v149, v237, v229
	v_mul_f32_e32 v148, 0x3fb8aa3b, v148
	v_mul_f32_e32 v149, 0x3fb8aa3b, v149
	v_exp_f32_e32 v148, v148
	v_exp_f32_e32 v149, v149
	s_nop 0
	v_pk_mul_f32 v[144:145], v[144:145], v[148:149]
	v_sub_f32_e32 v148, v150, v229
	v_sub_f32_e32 v149, v151, v229
	v_mul_f32_e32 v148, 0x3fb8aa3b, v148
	v_mul_f32_e32 v149, 0x3fb8aa3b, v149
	v_exp_f32_e32 v148, v148
	v_exp_f32_e32 v149, v149
	s_nop 0
	v_pk_mul_f32 v[130:131], v[130:131], v[148:149]
	v_sub_f32_e32 v148, v152, v229
	v_sub_f32_e32 v149, v153, v229
	v_mul_f32_e32 v148, 0x3fb8aa3b, v148
	v_mul_f32_e32 v149, 0x3fb8aa3b, v149
	v_exp_f32_e32 v148, v148
	v_exp_f32_e32 v149, v149
	v_cvt_pk_bf16_f32 v130, v130, v131
	v_pk_mul_f32 v[132:133], v[132:133], v[148:149]
	s_nop 0
	v_cvt_pk_bf16_f32 v131, v132, v133
	v_cvt_pk_bf16_f32 v132, v142, v143
	v_cvt_pk_bf16_f32 v133, v144, v145
	s_waitcnt lgkmcnt(0)
	s_nop 1
	v_mfma_f32_16x16x32_bf16 v[138:141], v[130:133], v[138:141], 0
	v_mfma_f32_16x16x32_bf16 v[134:137], v[130:133], v[134:137], 0
	v_mfma_f32_16x16x32_bf16 v[126:129], v[130:133], v[126:129], 0
	v_cvt_pk_bf16_f32 v130, v0, v1
	v_cvt_pk_bf16_f32 v131, v146, v147
	v_cvt_pk_bf16_f32 v132, v230, v231
	v_cvt_pk_bf16_f32 v133, v232, v233
	s_nop 1
	v_mfma_f32_16x16x32_bf16 v[118:121], v[130:133], v[118:121], v[138:141]
	v_mfma_f32_16x16x32_bf16 v[114:117], v[130:133], v[114:117], v[134:137]
	v_mfma_f32_16x16x32_bf16 v[122:125], v[130:133], v[122:125], v[126:129]
; template <int TT>
; DEV void mlstm_a_wave(LAS char* shm, const LAS char* kbuf, const bf16x8 (&qfr)[8], int fr, int fq, float m_prev, const LAS float* tpj, const LAS float* taj, f32x4 (&nacc)[3]) {
;     constexpr int VT = 67584, VRS = 96, NT = TT + 1;
;     const LAS char* kb = kbuf + fr * 512 + ((fq ^ (fr & 3)) << 4);
;     int xo[4];
; #pragma unroll
;     for (int b_ = 0; b_ < 4; ++b_) xo[b_] = ((b_ ^ (fr >> 2)) << 6);
;     ...
;     f32x4 sacc[NT];
; #pragma unroll
;     for (int jj = 0; jj < NT; ++jj) sacc[jj] = (f32x4){0.f, 0.f, 0.f, 0.f};
;     bf16x8 kf[NT];
; #pragma unroll
;     for (int jj = 0; jj < NT; ++jj) kf[jj] = *(const LAS bf16x8*)MLK_ADDR(jj, 0);
; #pragma unroll
;     for (int ks = 0; ks < 8; ++ks) {
;         bf16x8 kn[NT];
; #pragma unroll
;         for (int jj = 0; jj < NT; ++jj) kn[jj] = kf[jj];
;         if (ks < 7) {
; #pragma unroll
;             for (int jj = 0; jj < NT; ++jj) kn[jj] = *(const LAS bf16x8*)MLK_ADDR(jj, ks + 1);
;         }
; #pragma unroll
;         for (int jj = 0; jj < NT; ++jj) sacc[jj] = __builtin_amdgcn_mfma_f32_16x16x32_bf16(kf[jj], qfr[ks], sacc[jj], 0, 0, 0);
; #pragma unroll
;         for (int jj = 0; jj < NT; ++jj) kf[jj] = kn[jj];
;     }
;     ...
;     constexpr int NK = (TT >= 2) ? 2 : 1;
;     s16x4 vlo[NK][3], vhi[NK][3];
; #pragma unroll
;     for (int kk = 0; kk < NK; ++kk)
; #pragma unroll
;         for (int vt = 0; vt < 3; ++vt) {
;             vlo[kk][vt] = __builtin_amdgcn_ds_read_tr16_b64_v4i16((LAS s16x4*)(shm + VT + (32 * kk + 4 * fq + (fr >> 2)) * VRS + (16 * vt + 4 * (fr & 3)) * 2));
;             vhi[kk][vt] = __builtin_amdgcn_ds_read_tr16_b64_v4i16((LAS s16x4*)(shm + VT + (32 * kk + 16 + 4 * fq + (fr >> 2)) * VRS + (16 * vt + 4 * (fr & 3)) * 2));
;         }
;     const int t = 16 * TT + fr;
;     const float btm = -fmaxf(m_prev, tpj[t]);
;     f32x4 sm[2 * NK];
; #pragma unroll
;     for (int jj = 0; jj < 2 * NK; ++jj) {
;         if (jj < NT) {
;             const f32x4 a4 = *(const LAS f32x4*)(taj + 16 * jj + 4 * fq);
; #pragma unroll
;             for (int r = 0; r < 4; ++r) {
;                 const int s_ = 16 * jj + 4 * fq + r;
;                 sm[jj][r] = (jj < TT || s_ <= t) ? sacc[jj < NT ? jj : 0][r] * __expf(btm + a4[r]) : 0.f;
;             }
;         } else sm[jj] = (f32x4){0.f, 0.f, 0.f, 0.f};
;     }
; #pragma unroll
;     for (int kk = 0; kk < NK; ++kk) {
.LBB0_656:
	s_andn2_b64 vcc, exec, s[0:1]
	s_cbranch_vccnz .LBB0_658
	s_nop 4
	v_add_u32_e32 v1, s40, v203
	v_add_u32_e32 v1, 0x23580, v1
	ds_read_b32 v238, v1
	v_add_u32_e32 v0, s40, v202
	v_add_u32_e32 v1, 0x21500, v0
	ds_read_b128 v[250:253], v1
	v_add_u32_e32 v1, 0x21540, v0
	ds_read_b128 v[230:233], v1
	v_add_u32_e32 v1, 0x21580, v0
	ds_read_b128 v[234:237], v1
	ds_read_b128 v[114:117], v4 offset:8192
	ds_read_b128 v[118:121], v4 offset:16384
	v_add_u32_e32 v0, v5, v183
	ds_read_b128 v[122:125], v0
	ds_read_b128 v[126:129], v0 offset:8192
	ds_read_b128 v[130:133], v0 offset:16384
	s_waitcnt lgkmcnt(3)
	v_mfma_f32_16x16x32_bf16 v[134:137], v[110:113], v[38:41], 0
	v_add_u32_e32 v1, v5, v184
	ds_read_b128 v[138:141], v1
	ds_read_b128 v[142:145], v1 offset:8192
	ds_read_b128 v[146:149], v1 offset:16384
	v_add_u32_e32 v150, v5, v185
	v_mfma_f32_16x16x32_bf16 v[114:117], v[114:117], v[38:41], 0
	v_mfma_f32_16x16x32_bf16 v[118:121], v[118:121], v[38:41], 0
	s_waitcnt lgkmcnt(3)
	v_mfma_f32_16x16x32_bf16 v[122:125], v[122:125], v[34:37], v[134:137]
	v_mfma_f32_16x16x32_bf16 v[114:117], v[126:129], v[34:37], v[114:117]
	v_mfma_f32_16x16x32_bf16 v[118:121], v[130:133], v[34:37], v[118:121]
	ds_read_b128 v[126:129], v150
	ds_read_b128 v[130:133], v150 offset:8192
	ds_read_b128 v[134:137], v150 offset:16384
	s_waitcnt lgkmcnt(3)
	v_mfma_f32_16x16x32_bf16 v[122:125], v[138:141], v[30:33], v[122:125]
	v_mfma_f32_16x16x32_bf16 v[114:117], v[142:145], v[30:33], v[114:117]
	v_mfma_f32_16x16x32_bf16 v[118:121], v[146:149], v[30:33], v[118:121]
	ds_read_b128 v[138:141], v4 offset:256
	ds_read_b128 v[142:145], v4 offset:8448
	ds_read_b128 v[146:149], v4 offset:16640
	s_waitcnt lgkmcnt(3)
	v_mfma_f32_16x16x32_bf16 v[122:125], v[126:129], v[10:13], v[122:125]
	v_mfma_f32_16x16x32_bf16 v[114:117], v[130:133], v[10:13], v[114:117]
	v_mfma_f32_16x16x32_bf16 v[118:121], v[134:137], v[10:13], v[118:121]
	ds_read_b128 v[126:129], v0 offset:256
	ds_read_b128 v[130:133], v0 offset:8448
	ds_read_b128 v[134:137], v0 offset:16640
	v_add_u32_e32 v0, v187, v186
	s_waitcnt lgkmcnt(3)
	v_mfma_f32_16x16x32_bf16 v[122:125], v[138:141], v[26:29], v[122:125]
	v_mfma_f32_16x16x32_bf16 v[114:117], v[142:145], v[26:29], v[114:117]
	v_mfma_f32_16x16x32_bf16 v[118:121], v[146:149], v[26:29], v[118:121]
	ds_read_b128 v[138:141], v1 offset:256
	ds_read_b128 v[142:145], v1 offset:8448
	ds_read_b128 v[146:149], v1 offset:16640
	s_waitcnt lgkmcnt(3)
	v_mfma_f32_16x16x32_bf16 v[122:125], v[126:129], v[22:25], v[122:125]
	v_mfma_f32_16x16x32_bf16 v[114:117], v[130:133], v[22:25], v[114:117]
	v_mfma_f32_16x16x32_bf16 v[118:121], v[134:137], v[22:25], v[118:121]
	ds_read_b128 v[126:129], v150 offset:256
	ds_read_b128 v[130:133], v150 offset:8448
	ds_read_b128 v[134:137], v150 offset:16640
	s_waitcnt lgkmcnt(3)
	v_mfma_f32_16x16x32_bf16 v[122:125], v[138:141], v[14:17], v[122:125]
	v_mfma_f32_16x16x32_bf16 v[114:117], v[142:145], v[14:17], v[114:117]
	v_mfma_f32_16x16x32_bf16 v[118:121], v[146:149], v[14:17], v[118:121]
	s_waitcnt lgkmcnt(0)
	v_mfma_f32_16x16x32_bf16 v[142:145], v[126:129], v[18:21], v[122:125]
	v_mfma_f32_16x16x32_bf16 v[130:133], v[130:133], v[18:21], v[114:117]
	v_mfma_f32_16x16x32_bf16 v[146:149], v[134:137], v[18:21], v[118:121]
	s_nop 0
	ds_read_b64_tr_b16 v[140:141], v0 offset:1536
	ds_read_b64_tr_b16 v[138:139], v0
	ds_read_b64_tr_b16 v[134:135], v0 offset:32
	ds_read_b64_tr_b16 v[136:137], v0 offset:1568
	ds_read_b64_tr_b16 v[126:127], v0 offset:64
	ds_read_b64_tr_b16 v[128:129], v0 offset:1600
	ds_read_b64_tr_b16 v[118:119], v0 offset:3072
	ds_read_b64_tr_b16 v[120:121], v0 offset:4608
	ds_read_b64_tr_b16 v[114:115], v0 offset:3104
	ds_read_b64_tr_b16 v[116:117], v0 offset:4640
	ds_read_b64_tr_b16 v[122:123], v0 offset:3136
	ds_read_b64_tr_b16 v[124:125], v0 offset:4672
	s_waitcnt lgkmcnt(12)
	v_max_f32_e32 v0, v238, v238
	v_max_f32_e32 v229, v227, v0
	s_nop 0
	v_sub_f32_e32 v0, v234, v229
	v_mul_f32_e32 v0, 0x3fb8aa3b, v0
	v_exp_f32_e32 v0, v0
	v_sub_f32_e32 v1, v237, v229
	v_mul_f32_e32 v1, 0x3fb8aa3b, v1
	v_exp_f32_e32 v1, v1
	v_mul_f32_e32 v0, v146, v0
	v_cndmask_b32_e64 v234, v0, 0, s[6:7]
	v_sub_f32_e32 v0, v235, v229
	v_mul_f32_e32 v0, 0x3fb8aa3b, v0
	v_exp_f32_e32 v0, v0
	v_sub_f32_e32 v146, v250, v229
	v_mul_f32_e32 v146, 0x3fb8aa3b, v146
	v_exp_f32_e32 v146, v146
	v_mul_f32_e32 v0, v147, v0
	v_sub_f32_e32 v147, v251, v229
	v_mul_f32_e32 v147, 0x3fb8aa3b, v147
	v_exp_f32_e32 v147, v147
	v_cndmask_b32_e64 v235, v0, 0, s[14:15]
	v_sub_f32_e32 v0, v236, v229
	v_mul_f32_e32 v0, 0x3fb8aa3b, v0
	v_pk_mul_f32 v[142:143], v[142:143], v[146:147]
	v_sub_f32_e32 v146, v252, v229
	v_sub_f32_e32 v147, v253, v229
	v_mul_f32_e32 v146, 0x3fb8aa3b, v146
	v_mul_f32_e32 v147, 0x3fb8aa3b, v147
	v_exp_f32_e32 v146, v146
	v_exp_f32_e32 v147, v147
	v_exp_f32_e32 v0, v0
	v_pk_mul_f32 v[144:145], v[144:145], v[146:147]
	v_sub_f32_e32 v146, v230, v229
	v_sub_f32_e32 v147, v231, v229
	v_mul_f32_e32 v146, 0x3fb8aa3b, v146
	v_mul_f32_e32 v147, 0x3fb8aa3b, v147
	v_exp_f32_e32 v146, v146
	v_exp_f32_e32 v147, v147
	v_pk_mul_f32 v[0:1], v[148:149], v[0:1]
	v_pk_mul_f32 v[146:147], v[130:131], v[146:147]
	v_sub_f32_e32 v130, v232, v229
	v_sub_f32_e32 v131, v233, v229
	v_mul_f32_e32 v130, 0x3fb8aa3b, v130
	v_mul_f32_e32 v131, 0x3fb8aa3b, v131
	v_exp_f32_e32 v130, v130
	v_exp_f32_e32 v131, v131
	v_cvt_pk_bf16_f32 v0, v0, v1
	v_cndmask_b32_e64 v1, v0, 0, s[18:19]
	v_lshrrev_b32_e32 v0, 16, v0
	v_pk_mul_f32 v[148:149], v[132:133], v[130:131]
	v_cvt_pk_bf16_f32 v130, v142, v143
	v_cvt_pk_bf16_f32 v131, v144, v145
	v_cvt_pk_bf16_f32 v132, v146, v147
	v_cvt_pk_bf16_f32 v133, v148, v149
	v_cndmask_b32_e64 v0, v0, 0, s[16:17]
	s_waitcnt lgkmcnt(0)
	s_nop 0
	v_mfma_f32_16x16x32_bf16 v[138:141], v[130:133], v[138:141], 0
	v_mfma_f32_16x16x32_bf16 v[134:137], v[130:133], v[134:137], 0
	v_mfma_f32_16x16x32_bf16 v[126:129], v[130:133], v[126:129], 0
	v_cvt_pk_bf16_f32 v130, v234, v235
	v_perm_b32 v131, v0, v1, s60
	v_mov_b32_e32 v132, v3
	v_mov_b32_e32 v133, v3
	s_nop 1
	v_mfma_f32_16x16x32_bf16 v[118:121], v[130:133], v[118:121], v[138:141]
	v_mfma_f32_16x16x32_bf16 v[114:117], v[130:133], v[114:117], v[134:137]
	v_mfma_f32_16x16x32_bf16 v[122:125], v[130:133], v[122:125], v[126:129]

; #define LAS __attribute__((address_space(3)))
; #define gpart ((float*)S7(IPRE_OFF))
; template <int SKIP>
; DEV void mlstm_phase(LAS char* shm, const bf16_t* q, const bf16_t* k, const bf16_t* v, const float* gpart, const float* b_ig, const float* b_fg, bf16_t* hc, const bool pre) {
;     ...
;         const int vs = (item >> 3) & 7, bh = (item & 7) + 8 * (item >> 6), h = bh & 3, b = bh >> 2;
;         const size_t cb0 = ((size_t)(b * SEQ)) * DM + h * DH;
;         __syncthreads();
;         unsigned kvoff; { const int rw = 2 * wid + (lane >> 5); kvoff = (unsigned)(rw * DM + (((lane & 31) ^ rw) * 8)) * 2u; asm volatile("" : "+v"(kvoff)); }
;     ...
;         MLK_ISSUE(cb0, 0);
;         bf16x8 qfr[8];
;         const bf16_t* qfb = q + ((size_t)((b * 4 + h) * 32) * 4 + (wid & 3)) * 4096 + lane * 8;
; #pragma unroll
;         for (int ks = 0; ks < 8; ++ks) qfr[ks] = *(const bf16x8*)(qfb + ks * 512);
;         uint4 vv = make_uint4(0, 0, 0, 0);
;         if (wid < 4) vv = *(const uint4*)(v + cb0 + (size_t)(tid >> 2) * DM + vs * 32 + (tid & 3) * 8);
;         for (int i = tid; i < (CB + 25344 - VT) / 4; i += 512) ((LAS unsigned*)(shm + VT))[i] = 0u;
;         if (!(pre && item == (int)blockIdx.x)) mlstm_gate_scans(shm, gpart, b_ig, b_fg, item);
;         __syncthreads();
;         if (wid == 0) *(LAS unsigned*)(shm + VT + tid * VRS + 64) = 0x3F80u;
;         const int ndt = (wid == 0 || wid == 4 || wid == 1) ? 3 : ((wid == 5 || wid == 2) ? 2 : 1);
;         const int dt0 = (wid == 0) ? 0 : (wid == 4) ? 3 : (wid == 1) ? 6 : (wid == 5) ? 9 : (wid == 2) ? 11 : (wid == 6) ? 13 : (wid == 3) ? 14 : 15;
;         f32x4 cacc[3][3];
; #pragma unroll
;         for (int i = 0; i < 3; ++i)
; #pragma unroll
;             for (int vt = 0; vt < 3; ++vt) cacc[i][vt] = (f32x4){0.f, 0.f, 0.f, 0.f};
;         float m_prev = 0.f;
; #pragma nounroll
;         for (int j = 0; j < SEQ / CHUNK; ++j) {
;             const size_t cb = cb0 + (size_t)j * CHUNK * DM;
;             const float btot = __int_as_float(__builtin_amdgcn_readfirstlane(__float_as_int(tc[2 * j]))), amax = __int_as_float(__builtin_amdgcn_readfirstlane(__float_as_int(tc[2 * j + 1])));
.LBB0_1485:
	s_bfe_u32 s0, s91, 0x10002
	s_lshl_b32 s1, s0, 11
	s_lshl_b32 s40, s0, 2
	s_and_b32 s0, s77, 7
	s_lshl_b32 s41, s0, 6
	s_lshl_b32 s0, s38, 1
	s_and_b32 s39, s79, 3
	v_bitop3_b32 v0, s0, v189, v188 bitop3:0x36
	s_lshl_b32 s64, s39, 9
	v_lshlrev_b32_e32 v167, 4, v0
	v_bitop3_b32 v0, s0, v191, v188 bitop3:0x36
	v_lshlrev_b32_e32 v220, 4, v0
	s_cmp_gt_u32 s36, 1
	v_add_u32_e32 v0, s0, v196
	s_cselect_b64 s[34:35], -1, 0
	v_xor_b32_e32 v1, v0, v189
	v_xor_b32_e32 v0, v0, v191
	s_cmp_eq_u32 s36, 3
	v_lshlrev_b32_e32 v222, 4, v0
	s_cselect_b64 s[36:37], -1, 0
	v_add_u32_e32 v0, s0, v197
	s_lshl_b32 s0, s76, 9
	s_and_b32 s0, s0, 0xfffff000
	s_or_b32 s0, s0, s1
	s_ashr_i32 s1, s0, 31
	s_lshl_b64 s[28:29], s[0:1], 11
	s_add_u32 s30, s53, s28
	s_addc_u32 s31, s55, s29
	v_lshl_add_u64 v[168:169], s[30:31], 0, v[2:3]
	s_add_i32 s30, s52, s40
	v_lshlrev_b32_e32 v221, 4, v1
	v_xor_b32_e32 v1, v0, v189
	v_xor_b32_e32 v0, v0, v191
	s_add_i32 s30, s30, s39
	v_lshlrev_b32_e32 v223, 4, v1
	v_lshlrev_b32_e32 v224, 4, v0
	s_lshl_b32 s30, s30, 5
	v_lshl_add_u64 v[0:1], v[158:159], 0, s[0:1]
	v_lshl_add_u32 v54, s38, 5, v192
	s_ashr_i32 s31, s30, 31
	v_lshlrev_b64 v[0:1], 11, v[0:1]
	v_mov_b32_e32 v4, v3
	v_mov_b32_e32 v5, v3
	s_lshl_b64 s[30:31], s[30:31], 15
	s_or_b32 s28, s28, s41
	v_or_b32_e32 v0, s41, v0
	v_mov_b32_e32 v2, v3
	v_add_u32_e32 v225, v54, v178
	v_add_u32_e32 v226, v54, v195
	v_mov_b64_e32 v[64:65], v[4:5]
	v_mov_b64_e32 v[68:69], v[4:5]
	v_mov_b64_e32 v[56:57], v[4:5]
	v_mov_b64_e32 v[72:73], v[4:5]
	v_mov_b64_e32 v[76:77], v[4:5]
	v_mov_b64_e32 v[60:61], v[4:5]
	v_lshl_add_u64 v[170:171], v[154:155], 0, s[30:31]
	v_lshl_add_u64 v[172:173], v[162:163], 0, s[28:29]
	v_lshl_add_u64 v[174:175], v[164:165], 0, v[0:1]
	s_mov_b32 s28, 0
	s_movk_i32 s40, 0xe000
	s_mov_b64 s[38:39], 0
	v_mov_b32_e32 v42, 0
	v_mov_b32_e32 v43, 0
	v_mov_b32_e32 v44, 0
	v_mov_b32_e32 v45, 0
	v_mov_b32_e32 v46, 0
	v_mov_b32_e32 v47, 0
	v_mov_b32_e32 v48, 0
	v_mov_b32_e32 v49, 0
	v_mov_b32_e32 v50, 0
	v_mov_b32_e32 v51, 0
	v_mov_b32_e32 v52, 0
	v_mov_b32_e32 v53, 0
	s_mov_b32 s41, s54
	v_mov_b64_e32 v[62:63], v[2:3]
	v_mov_b64_e32 v[66:67], v[2:3]
	v_mov_b64_e32 v[54:55], v[2:3]
	v_mov_b64_e32 v[70:71], v[2:3]
	v_mov_b64_e32 v[74:75], v[2:3]
	v_mov_b64_e32 v[58:59], v[2:3]
	s_add_i32 s0, s41, -4
	v_mov_b32_e32 v0, s0
	ds_read_b32 v252, v0
	ds_read_b32 v253, v0 offset:4
	s_waitcnt lgkmcnt(0)
	s_branch .LBB0_1487

; template <int SKIP>
; DEV void mlstm_phase(LAS char* shm, const bf16_t* q, const bf16_t* k, const bf16_t* v, const float* gpart, const float* b_ig, const float* b_fg, bf16_t* hc, const bool pre) {
;     ...
;         for (int j = 0; j < SEQ / CHUNK; ++j) {
;             const size_t cb = cb0 + (size_t)j * CHUNK * DM;
;             const float btot = __int_as_float(__builtin_amdgcn_readfirstlane(__float_as_int(tc[2 * j]))), amax = __int_as_float(__builtin_amdgcn_readfirstlane(__float_as_int(tc[2 * j + 1])));
;             const float mxc = __int_as_float(__builtin_amdgcn_readfirstlane(__float_as_int(fmaxf(m_prev, amax))));
.LBB0_1487:
	s_add_i32 s0, s41, 4
	v_mov_b32_e32 v0, s0
	v_max_f32_e64 v227, s28, s28
	s_mov_b64 s[0:1], -1
	s_and_b64 vcc, exec, s[70:71]
	v_readfirstlane_b32 s29, v253
	v_readfirstlane_b32 s42, v252
	ds_read_b32 v252, v0
	ds_read_b32 v253, v0 offset:4
	v_max_f32_e64 v0, s29, s29
	v_max_f32_e32 v0, v227, v0
	s_nop 0
	v_readfirstlane_b32 s43, v0
	s_cbranch_vccnz .LBB0_1494
	s_andn2_b64 vcc, exec, s[0:1]
	s_cbranch_vccz .LBB0_1495

; #define LAS __attribute__((address_space(3)))
; template <int TT>
; DEV void mlstm_a_wave(LAS char* shm, const LAS char* kbuf, const bf16x8 (&qfr)[8], int fr, int fq, float m_prev, const LAS float* tpj, const LAS float* taj, f32x4 (&nacc)[3]) {
;     constexpr int VT = 67584, VRS = 96, NT = TT + 1;
;     const LAS char* kb = kbuf + fr * 512 + ((fq ^ (fr & 3)) << 4);
;     int xo[4];
; #pragma unroll
;     for (int b_ = 0; b_ < 4; ++b_) xo[b_] = ((b_ ^ (fr >> 2)) << 6);
;     ...
;     f32x4 sacc[NT];
; #pragma unroll
;     for (int jj = 0; jj < NT; ++jj) sacc[jj] = (f32x4){0.f, 0.f, 0.f, 0.f};
;     bf16x8 kf[NT];
; #pragma unroll
;     for (int jj = 0; jj < NT; ++jj) kf[jj] = *(const LAS bf16x8*)MLK_ADDR(jj, 0);
; #pragma unroll
;     for (int ks = 0; ks < 8; ++ks) {
;         bf16x8 kn[NT];
; #pragma unroll
;         for (int jj = 0; jj < NT; ++jj) kn[jj] = kf[jj];
;         if (ks < 7) {
; #pragma unroll
;             for (int jj = 0; jj < NT; ++jj) kn[jj] = *(const LAS bf16x8*)MLK_ADDR(jj, ks + 1);
;         }
; #pragma unroll
;         for (int jj = 0; jj < NT; ++jj) sacc[jj] = __builtin_amdgcn_mfma_f32_16x16x32_bf16(kf[jj], qfr[ks], sacc[jj], 0, 0, 0);
; #pragma unroll
;         for (int jj = 0; jj < NT; ++jj) kf[jj] = kn[jj];
;     }
;     ...
;     constexpr int NK = (TT >= 2) ? 2 : 1;
;     s16x4 vlo[NK][3], vhi[NK][3];
; #pragma unroll
;     for (int kk = 0; kk < NK; ++kk)
; #pragma unroll
;         for (int vt = 0; vt < 3; ++vt) {
;             vlo[kk][vt] = __builtin_amdgcn_ds_read_tr16_b64_v4i16((LAS s16x4*)(shm + VT + (32 * kk + 4 * fq + (fr >> 2)) * VRS + (16 * vt + 4 * (fr & 3)) * 2));
;             vhi[kk][vt] = __builtin_amdgcn_ds_read_tr16_b64_v4i16((LAS s16x4*)(shm + VT + (32 * kk + 16 + 4 * fq + (fr >> 2)) * VRS + (16 * vt + 4 * (fr & 3)) * 2));
;         }
;     const int t = 16 * TT + fr;
;     const float btm = -fmaxf(m_prev, tpj[t]);
;     f32x4 sm[2 * NK];
; #pragma unroll
;     for (int jj = 0; jj < 2 * NK; ++jj) {
;         if (jj < NT) {
;             const f32x4 a4 = *(const LAS f32x4*)(taj + 16 * jj + 4 * fq);
.LBB0_1503:
	s_and_b32 s29, s38, 0x8000
	s_andn2_b64 vcc, exec, s[0:1]
	s_add_i32 s29, s29, 0
	s_cbranch_vccnz .LBB0_1515
	v_add3_u32 v5, s29, v180, v181
	v_add_u32_e32 v4, v5, v182
	ds_read_b128 v[110:113], v4
	s_cmp_lt_i32 s61, 2
	s_mov_b64 s[0:1], -1
	s_cbranch_scc1 .LBB0_1510
	s_cmp_gt_i32 s61, 2
	s_cbranch_scc0 .LBB0_1507
	v_add_u32_e32 v1, s40, v203
	v_add_u32_e32 v1, 0x235c0, v1
	ds_read_b32 v246, v1
	v_add_u32_e32 v0, s40, v202
	v_add_u32_e32 v1, 0x21580, v0
	ds_read_b128 v[248:251], v1
	v_add_u32_e32 v1, 0x215c0, v0
	ds_read_b128 v[242:245], v1
	ds_read_b128 v[114:117], v4 offset:8192
	ds_read_b128 v[118:121], v4 offset:16384
	ds_read_b128 v[122:125], v4 offset:24576
	v_add_u32_e32 v0, v5, v183
	ds_read_b128 v[126:129], v0
	ds_read_b128 v[130:133], v0 offset:8192
	ds_read_b128 v[134:137], v0 offset:16384
	ds_read_b128 v[138:141], v0 offset:24576
	s_waitcnt lgkmcnt(4)
	v_mfma_f32_16x16x32_bf16 v[142:145], v[110:113], v[38:41], 0
	v_add_u32_e32 v1, v5, v184
	ds_read_b128 v[146:149], v1
	ds_read_b128 v[150:153], v1 offset:8192
	ds_read_b128 v[230:233], v1 offset:16384
	ds_read_b128 v[234:237], v1 offset:24576
	v_add_u32_e32 v229, v5, v185
	v_mfma_f32_16x16x32_bf16 v[114:117], v[114:117], v[38:41], 0
	s_mov_b64 s[0:1], 0
	v_mfma_f32_16x16x32_bf16 v[118:121], v[118:121], v[38:41], 0
	v_mfma_f32_16x16x32_bf16 v[122:125], v[122:125], v[38:41], 0
	s_waitcnt lgkmcnt(4)
	v_mfma_f32_16x16x32_bf16 v[126:129], v[126:129], v[34:37], v[142:145]
	v_mfma_f32_16x16x32_bf16 v[114:117], v[130:133], v[34:37], v[114:117]
	v_mfma_f32_16x16x32_bf16 v[118:121], v[134:137], v[34:37], v[118:121]
	v_mfma_f32_16x16x32_bf16 v[122:125], v[138:141], v[34:37], v[122:125]
	ds_read_b128 v[130:133], v229
	ds_read_b128 v[134:137], v229 offset:8192
	ds_read_b128 v[138:141], v229 offset:16384
	ds_read_b128 v[142:145], v229 offset:24576
	s_waitcnt lgkmcnt(4)
	v_mfma_f32_16x16x32_bf16 v[126:129], v[146:149], v[30:33], v[126:129]
	v_mfma_f32_16x16x32_bf16 v[114:117], v[150:153], v[30:33], v[114:117]
	v_mfma_f32_16x16x32_bf16 v[118:121], v[230:233], v[30:33], v[118:121]
	v_mfma_f32_16x16x32_bf16 v[122:125], v[234:237], v[30:33], v[122:125]
	ds_read_b128 v[146:149], v4 offset:256
	ds_read_b128 v[150:153], v4 offset:8448
	ds_read_b128 v[230:233], v4 offset:16640
	ds_read_b128 v[234:237], v4 offset:24832
	s_waitcnt lgkmcnt(4)
	v_mfma_f32_16x16x32_bf16 v[126:129], v[130:133], v[10:13], v[126:129]
	v_mfma_f32_16x16x32_bf16 v[114:117], v[134:137], v[10:13], v[114:117]
	v_mfma_f32_16x16x32_bf16 v[118:121], v[138:141], v[10:13], v[118:121]
	v_mfma_f32_16x16x32_bf16 v[122:125], v[142:145], v[10:13], v[122:125]
	ds_read_b128 v[130:133], v0 offset:256
	ds_read_b128 v[134:137], v0 offset:8448
	ds_read_b128 v[138:141], v0 offset:16640
	ds_read_b128 v[142:145], v0 offset:24832
	v_add_u32_e32 v0, v187, v186
	s_waitcnt lgkmcnt(4)
	v_mfma_f32_16x16x32_bf16 v[126:129], v[146:149], v[26:29], v[126:129]
	v_mfma_f32_16x16x32_bf16 v[114:117], v[150:153], v[26:29], v[114:117]
	v_mfma_f32_16x16x32_bf16 v[118:121], v[230:233], v[26:29], v[118:121]
	v_mfma_f32_16x16x32_bf16 v[122:125], v[234:237], v[26:29], v[122:125]
	ds_read_b128 v[146:149], v1 offset:256
	ds_read_b128 v[150:153], v1 offset:8448
	ds_read_b128 v[230:233], v1 offset:16640
	ds_read_b128 v[234:237], v1 offset:24832
	s_waitcnt lgkmcnt(4)
	v_mfma_f32_16x16x32_bf16 v[126:129], v[130:133], v[22:25], v[126:129]
	v_mfma_f32_16x16x32_bf16 v[114:117], v[134:137], v[22:25], v[114:117]
	v_mfma_f32_16x16x32_bf16 v[118:121], v[138:141], v[22:25], v[118:121]
	ds_read_b128 v[130:133], v229 offset:256
	ds_read_b128 v[134:137], v229 offset:8448
	ds_read_b128 v[138:141], v229 offset:16640
	ds_read_b128 v[238:241], v229 offset:24832
	v_mfma_f32_16x16x32_bf16 v[122:125], v[142:145], v[22:25], v[122:125]
	s_waitcnt lgkmcnt(4)
	v_mfma_f32_16x16x32_bf16 v[126:129], v[146:149], v[14:17], v[126:129]
	v_mfma_f32_16x16x32_bf16 v[114:117], v[150:153], v[14:17], v[114:117]
	v_mfma_f32_16x16x32_bf16 v[118:121], v[230:233], v[14:17], v[118:121]
	v_mfma_f32_16x16x32_bf16 v[122:125], v[234:237], v[14:17], v[122:125]
	s_waitcnt lgkmcnt(0)
	v_mfma_f32_16x16x32_bf16 v[130:133], v[130:133], v[18:21], v[126:129]
	v_mfma_f32_16x16x32_bf16 v[142:145], v[134:137], v[18:21], v[114:117]
	v_mfma_f32_16x16x32_bf16 v[146:149], v[138:141], v[18:21], v[118:121]
	v_mfma_f32_16x16x32_bf16 v[230:233], v[238:241], v[18:21], v[122:125]
	s_nop 0
	v_add_u32_e32 v5, s40, v202
	v_add_u32_e32 v1, 0x21500, v5
	ds_read_b128 v[150:153], v1
	v_add_u32_e32 v1, 0x21540, v5
	ds_read_b128 v[234:237], v1
	ds_read_b64_tr_b16 v[140:141], v0 offset:1536
	ds_read_b64_tr_b16 v[138:139], v0
	ds_read_b64_tr_b16 v[134:135], v0 offset:32
	ds_read_b64_tr_b16 v[136:137], v0 offset:1568
	ds_read_b64_tr_b16 v[126:127], v0 offset:64
	ds_read_b64_tr_b16 v[128:129], v0 offset:1600
	ds_read_b64_tr_b16 v[118:119], v0 offset:3072
	ds_read_b64_tr_b16 v[120:121], v0 offset:4608
	ds_read_b64_tr_b16 v[114:115], v0 offset:3104
	ds_read_b64_tr_b16 v[116:117], v0 offset:4640
	ds_read_b64_tr_b16 v[122:123], v0 offset:3136
	ds_read_b64_tr_b16 v[124:125], v0 offset:4672
	s_waitcnt lgkmcnt(12)
; DEV unsigned pk2(float lo, float hi) { f32n2 v = {lo, hi}; bf16n2 b = __builtin_convertvector(v, bf16n2); return __builtin_bit_cast(unsigned, b); }
; #define LAS __attribute__((address_space(3)))
; template <int TT>
; DEV void mlstm_a_wave(LAS char* shm, const LAS char* kbuf, const bf16x8 (&qfr)[8], int fr, int fq, float m_prev, const LAS float* tpj, const LAS float* taj, f32x4 (&nacc)[3]) {
;     ...
;     const int t = 16 * TT + fr;
;     const float btm = -fmaxf(m_prev, tpj[t]);
;     f32x4 sm[2 * NK];
; #pragma unroll
;     for (int jj = 0; jj < 2 * NK; ++jj) {
;         if (jj < NT) {
;             const f32x4 a4 = *(const LAS f32x4*)(taj + 16 * jj + 4 * fq);
; #pragma unroll
;             for (int r = 0; r < 4; ++r) {
;                 const int s_ = 16 * jj + 4 * fq + r;
;                 sm[jj][r] = (jj < TT || s_ <= t) ? sacc[jj < NT ? jj : 0][r] * __expf(btm + a4[r]) : 0.f;
;             }
;         } else sm[jj] = (f32x4){0.f, 0.f, 0.f, 0.f};
;     }
; #pragma unroll
;     for (int kk = 0; kk < NK; ++kk) {
;         const u32x4 u = (u32x4){pk2(sm[2 * kk][0], sm[2 * kk][1]), pk2(sm[2 * kk][2], sm[2 * kk][3]), pk2(sm[2 * kk + 1][0], sm[2 * kk + 1][1]), pk2(sm[2 * kk + 1][2], sm[2 * kk + 1][3])};
;         const bf16x8 af = *(const bf16x8*)&u;
; #pragma unroll
;         for (int vt = 0; vt < 3; ++vt) {
;             bf16x8 bv8; bv8[0] = vlo[kk][vt][0]; bv8[1] = vlo[kk][vt][1]; bv8[2] = vlo[kk][vt][2]; bv8[3] = vlo[kk][vt][3];
;             bv8[4] = vhi[kk][vt][0]; bv8[5] = vhi[kk][vt][1]; bv8[6] = vhi[kk][vt][2]; bv8[7] = vhi[kk][vt][3];
;             nacc[vt] = __builtin_amdgcn_mfma_f32_16x16x32_bf16(af, bv8, nacc[vt], 0, 0, 0);
;         }
;     }
	v_max_f32_e32 v0, v246, v246
	v_max_f32_e32 v229, v227, v0
	s_nop 0
	v_sub_f32_e32 v1, v249, v229
	s_nop 0
	v_sub_f32_e32 v0, v242, v229
	v_mul_f32_e32 v0, 0x3fb8aa3b, v0
	v_exp_f32_e32 v0, v0
	v_mul_f32_e32 v1, 0x3fb8aa3b, v1
	v_exp_f32_e32 v1, v1
	v_mul_f32_e32 v0, v230, v0
	v_cndmask_b32_e64 v230, v0, 0, s[6:7]
	v_sub_f32_e32 v0, v243, v229
	v_mul_f32_e32 v0, 0x3fb8aa3b, v0
	v_exp_f32_e32 v0, v0
	s_nop 0
	v_mul_f32_e32 v0, v231, v0
	v_cndmask_b32_e64 v231, 0, v0, s[8:9]
	v_sub_f32_e32 v0, v244, v229
	v_mul_f32_e32 v0, 0x3fb8aa3b, v0
	v_exp_f32_e32 v0, v0
	s_nop 0
	v_mul_f32_e32 v0, v232, v0
	v_cndmask_b32_e64 v232, v0, 0, s[10:11]
	v_sub_f32_e32 v0, v245, v229
	v_mul_f32_e32 v0, 0x3fb8aa3b, v0
	v_exp_f32_e32 v0, v0
	s_nop 0
	v_mul_f32_e32 v0, v233, v0
	v_cndmask_b32_e64 v233, v0, 0, s[12:13]
	v_sub_f32_e32 v0, v248, v229
	v_mul_f32_e32 v0, 0x3fb8aa3b, v0
	v_exp_f32_e32 v0, v0
	s_nop 0
	v_pk_mul_f32 v[0:1], v[146:147], v[0:1]
	v_sub_f32_e32 v146, v250, v229
	v_sub_f32_e32 v147, v251, v229
	v_mul_f32_e32 v146, 0x3fb8aa3b, v146
	v_mul_f32_e32 v147, 0x3fb8aa3b, v147
	v_exp_f32_e32 v146, v146
	v_exp_f32_e32 v147, v147
	s_nop 0
	v_pk_mul_f32 v[146:147], v[148:149], v[146:147]
	v_sub_f32_e32 v148, v234, v229
	v_sub_f32_e32 v149, v235, v229
	v_mul_f32_e32 v148, 0x3fb8aa3b, v148
	v_mul_f32_e32 v149, 0x3fb8aa3b, v149
	v_exp_f32_e32 v148, v148
	v_exp_f32_e32 v149, v149
	s_nop 0
	v_pk_mul_f32 v[142:143], v[142:143], v[148:149]
	v_sub_f32_e32 v148, v236, v229
	v_sub_f32_e32 v149, v237, v229
	v_mul_f32_e32 v148, 0x3fb8aa3b, v148
	v_mul_f32_e32 v149, 0x3fb8aa3b, v149
	v_exp_f32_e32 v148, v148
	v_exp_f32_e32 v149, v149
	s_nop 0
	v_pk_mul_f32 v[144:145], v[144:145], v[148:149]
	v_sub_f32_e32 v148, v150, v229
	v_sub_f32_e32 v149, v151, v229
	v_mul_f32_e32 v148, 0x3fb8aa3b, v148
	v_mul_f32_e32 v149, 0x3fb8aa3b, v149
	v_exp_f32_e32 v148, v148
	v_exp_f32_e32 v149, v149
	s_nop 0
	v_pk_mul_f32 v[130:131], v[130:131], v[148:149]
	v_sub_f32_e32 v148, v152, v229
	v_sub_f32_e32 v149, v153, v229
	v_mul_f32_e32 v148, 0x3fb8aa3b, v148
	v_mul_f32_e32 v149, 0x3fb8aa3b, v149
	v_exp_f32_e32 v148, v148
	v_exp_f32_e32 v149, v149
	v_cvt_pk_bf16_f32 v130, v130, v131
	v_pk_mul_f32 v[132:133], v[132:133], v[148:149]
	s_nop 0
	v_cvt_pk_bf16_f32 v131, v132, v133
	v_cvt_pk_bf16_f32 v132, v142, v143
	v_cvt_pk_bf16_f32 v133, v144, v145
	s_waitcnt lgkmcnt(0)
	s_nop 1
	v_mfma_f32_16x16x32_bf16 v[138:141], v[130:133], v[138:141], 0
	v_mfma_f32_16x16x32_bf16 v[134:137], v[130:133], v[134:137], 0
	v_mfma_f32_16x16x32_bf16 v[126:129], v[130:133], v[126:129], 0
	v_cvt_pk_bf16_f32 v130, v0, v1
	v_cvt_pk_bf16_f32 v131, v146, v147
	v_cvt_pk_bf16_f32 v132, v230, v231
	v_cvt_pk_bf16_f32 v133, v232, v233
	s_nop 1
	v_mfma_f32_16x16x32_bf16 v[118:121], v[130:133], v[118:121], v[138:141]
	v_mfma_f32_16x16x32_bf16 v[114:117], v[130:133], v[114:117], v[134:137]
	v_mfma_f32_16x16x32_bf16 v[122:125], v[130:133], v[122:125], v[126:129]
; template <int TT>
; DEV void mlstm_a_wave(LAS char* shm, const LAS char* kbuf, const bf16x8 (&qfr)[8], int fr, int fq, float m_prev, const LAS float* tpj, const LAS float* taj, f32x4 (&nacc)[3]) {
;     constexpr int VT = 67584, VRS = 96, NT = TT + 1;
;     const LAS char* kb = kbuf + fr * 512 + ((fq ^ (fr & 3)) << 4);
;     int xo[4];
; #pragma unroll
;     for (int b_ = 0; b_ < 4; ++b_) xo[b_] = ((b_ ^ (fr >> 2)) << 6);
;     ...
;     f32x4 sacc[NT];
; #pragma unroll
;     for (int jj = 0; jj < NT; ++jj) sacc[jj] = (f32x4){0.f, 0.f, 0.f, 0.f};
;     bf16x8 kf[NT];
; #pragma unroll
;     for (int jj = 0; jj < NT; ++jj) kf[jj] = *(const LAS bf16x8*)MLK_ADDR(jj, 0);
; #pragma unroll
;     for (int ks = 0; ks < 8; ++ks) {
;         bf16x8 kn[NT];
; #pragma unroll
;         for (int jj = 0; jj < NT; ++jj) kn[jj] = kf[jj];
;         if (ks < 7) {
; #pragma unroll
;             for (int jj = 0; jj < NT; ++jj) kn[jj] = *(const LAS bf16x8*)MLK_ADDR(jj, ks + 1);
;         }
; #pragma unroll
;         for (int jj = 0; jj < NT; ++jj) sacc[jj] = __builtin_amdgcn_mfma_f32_16x16x32_bf16(kf[jj], qfr[ks], sacc[jj], 0, 0, 0);
; #pragma unroll
;         for (int jj = 0; jj < NT; ++jj) kf[jj] = kn[jj];
;     }
;     ...
;     constexpr int NK = (TT >= 2) ? 2 : 1;
;     s16x4 vlo[NK][3], vhi[NK][3];
; #pragma unroll
;     for (int kk = 0; kk < NK; ++kk)
; #pragma unroll
;         for (int vt = 0; vt < 3; ++vt) {
;             vlo[kk][vt] = __builtin_amdgcn_ds_read_tr16_b64_v4i16((LAS s16x4*)(shm + VT + (32 * kk + 4 * fq + (fr >> 2)) * VRS + (16 * vt + 4 * (fr & 3)) * 2));
;             vhi[kk][vt] = __builtin_amdgcn_ds_read_tr16_b64_v4i16((LAS s16x4*)(shm + VT + (32 * kk + 16 + 4 * fq + (fr >> 2)) * VRS + (16 * vt + 4 * (fr & 3)) * 2));
;         }
;     const int t = 16 * TT + fr;
;     const float btm = -fmaxf(m_prev, tpj[t]);
;     f32x4 sm[2 * NK];
; #pragma unroll
;     for (int jj = 0; jj < 2 * NK; ++jj) {
;         if (jj < NT) {
;             const f32x4 a4 = *(const LAS f32x4*)(taj + 16 * jj + 4 * fq);
; #pragma unroll
;             for (int r = 0; r < 4; ++r) {
;                 const int s_ = 16 * jj + 4 * fq + r;
;                 sm[jj][r] = (jj < TT || s_ <= t) ? sacc[jj < NT ? jj : 0][r] * __expf(btm + a4[r]) : 0.f;
;             }
;         } else sm[jj] = (f32x4){0.f, 0.f, 0.f, 0.f};
;     }
; #pragma unroll
;     for (int kk = 0; kk < NK; ++kk) {
.LBB0_1507:
	s_andn2_b64 vcc, exec, s[0:1]
	s_cbranch_vccnz .LBB0_1509
	s_nop 4
	v_add_u32_e32 v1, s40, v203
	v_add_u32_e32 v1, 0x23580, v1
	ds_read_b32 v246, v1
	v_add_u32_e32 v0, s40, v202
	v_add_u32_e32 v1, 0x21500, v0
	ds_read_b128 v[248:251], v1
	v_add_u32_e32 v1, 0x21540, v0
	ds_read_b128 v[230:233], v1
	v_add_u32_e32 v1, 0x21580, v0
	ds_read_b128 v[234:237], v1
	ds_read_b128 v[114:117], v4 offset:8192
	ds_read_b128 v[118:121], v4 offset:16384
	v_add_u32_e32 v0, v5, v183
	ds_read_b128 v[122:125], v0
	ds_read_b128 v[126:129], v0 offset:8192
	ds_read_b128 v[130:133], v0 offset:16384
	s_waitcnt lgkmcnt(3)
	v_mfma_f32_16x16x32_bf16 v[134:137], v[110:113], v[38:41], 0
	v_add_u32_e32 v1, v5, v184
	ds_read_b128 v[138:141], v1
	ds_read_b128 v[142:145], v1 offset:8192
	ds_read_b128 v[146:149], v1 offset:16384
	v_add_u32_e32 v150, v5, v185
	v_mfma_f32_16x16x32_bf16 v[114:117], v[114:117], v[38:41], 0
	v_mfma_f32_16x16x32_bf16 v[118:121], v[118:121], v[38:41], 0
	s_waitcnt lgkmcnt(3)
	v_mfma_f32_16x16x32_bf16 v[122:125], v[122:125], v[34:37], v[134:137]
	v_mfma_f32_16x16x32_bf16 v[114:117], v[126:129], v[34:37], v[114:117]
	v_mfma_f32_16x16x32_bf16 v[118:121], v[130:133], v[34:37], v[118:121]
	ds_read_b128 v[126:129], v150
	ds_read_b128 v[130:133], v150 offset:8192
	ds_read_b128 v[134:137], v150 offset:16384
	s_waitcnt lgkmcnt(3)
	v_mfma_f32_16x16x32_bf16 v[122:125], v[138:141], v[30:33], v[122:125]
	v_mfma_f32_16x16x32_bf16 v[114:117], v[142:145], v[30:33], v[114:117]
	v_mfma_f32_16x16x32_bf16 v[118:121], v[146:149], v[30:33], v[118:121]
	ds_read_b128 v[138:141], v4 offset:256
	ds_read_b128 v[142:145], v4 offset:8448
	ds_read_b128 v[146:149], v4 offset:16640
	s_waitcnt lgkmcnt(3)
	v_mfma_f32_16x16x32_bf16 v[122:125], v[126:129], v[10:13], v[122:125]
	v_mfma_f32_16x16x32_bf16 v[114:117], v[130:133], v[10:13], v[114:117]
	v_mfma_f32_16x16x32_bf16 v[118:121], v[134:137], v[10:13], v[118:121]
	ds_read_b128 v[126:129], v0 offset:256
	ds_read_b128 v[130:133], v0 offset:8448
	ds_read_b128 v[134:137], v0 offset:16640
	v_add_u32_e32 v0, v187, v186
	s_waitcnt lgkmcnt(3)
	v_mfma_f32_16x16x32_bf16 v[122:125], v[138:141], v[26:29], v[122:125]
	v_mfma_f32_16x16x32_bf16 v[114:117], v[142:145], v[26:29], v[114:117]
	v_mfma_f32_16x16x32_bf16 v[118:121], v[146:149], v[26:29], v[118:121]
	ds_read_b128 v[138:141], v1 offset:256
	ds_read_b128 v[142:145], v1 offset:8448
	ds_read_b128 v[146:149], v1 offset:16640
	s_waitcnt lgkmcnt(3)
	v_mfma_f32_16x16x32_bf16 v[122:125], v[126:129], v[22:25], v[122:125]
	v_mfma_f32_16x16x32_bf16 v[114:117], v[130:133], v[22:25], v[114:117]
	v_mfma_f32_16x16x32_bf16 v[118:121], v[134:137], v[22:25], v[118:121]
	ds_read_b128 v[126:129], v150 offset:256
	ds_read_b128 v[130:133], v150 offset:8448
	ds_read_b128 v[134:137], v150 offset:16640
	s_waitcnt lgkmcnt(3)
	v_mfma_f32_16x16x32_bf16 v[122:125], v[138:141], v[14:17], v[122:125]
	v_mfma_f32_16x16x32_bf16 v[114:117], v[142:145], v[14:17], v[114:117]
	v_mfma_f32_16x16x32_bf16 v[118:121], v[146:149], v[14:17], v[118:121]
	s_waitcnt lgkmcnt(0)
	v_mfma_f32_16x16x32_bf16 v[142:145], v[126:129], v[18:21], v[122:125]
	v_mfma_f32_16x16x32_bf16 v[130:133], v[130:133], v[18:21], v[114:117]
	v_mfma_f32_16x16x32_bf16 v[146:149], v[134:137], v[18:21], v[118:121]
	s_nop 0
	ds_read_b64_tr_b16 v[140:141], v0 offset:1536
	ds_read_b64_tr_b16 v[138:139], v0
	ds_read_b64_tr_b16 v[134:135], v0 offset:32
	ds_read_b64_tr_b16 v[136:137], v0 offset:1568
	ds_read_b64_tr_b16 v[126:127], v0 offset:64
	ds_read_b64_tr_b16 v[128:129], v0 offset:1600
	ds_read_b64_tr_b16 v[118:119], v0 offset:3072
	ds_read_b64_tr_b16 v[120:121], v0 offset:4608
	ds_read_b64_tr_b16 v[114:115], v0 offset:3104
	ds_read_b64_tr_b16 v[116:117], v0 offset:4640
	ds_read_b64_tr_b16 v[122:123], v0 offset:3136
	ds_read_b64_tr_b16 v[124:125], v0 offset:4672
	s_waitcnt lgkmcnt(12)
	v_max_f32_e32 v0, v246, v246
	v_max_f32_e32 v229, v227, v0
	s_nop 0
	v_sub_f32_e32 v0, v234, v229
	v_mul_f32_e32 v0, 0x3fb8aa3b, v0
	v_exp_f32_e32 v0, v0
	v_sub_f32_e32 v1, v237, v229
	v_mul_f32_e32 v1, 0x3fb8aa3b, v1
	v_exp_f32_e32 v1, v1
	v_mul_f32_e32 v0, v146, v0
	v_cndmask_b32_e64 v234, v0, 0, s[6:7]
	v_sub_f32_e32 v0, v235, v229
	v_mul_f32_e32 v0, 0x3fb8aa3b, v0
	v_exp_f32_e32 v0, v0
	v_sub_f32_e32 v146, v248, v229
	v_mul_f32_e32 v146, 0x3fb8aa3b, v146
	v_exp_f32_e32 v146, v146
	v_mul_f32_e32 v0, v147, v0
	v_sub_f32_e32 v147, v249, v229
	v_mul_f32_e32 v147, 0x3fb8aa3b, v147
	v_exp_f32_e32 v147, v147
	v_cndmask_b32_e64 v235, v0, 0, s[14:15]
	v_sub_f32_e32 v0, v236, v229
	v_mul_f32_e32 v0, 0x3fb8aa3b, v0
	v_pk_mul_f32 v[142:143], v[142:143], v[146:147]
	v_sub_f32_e32 v146, v250, v229
	v_sub_f32_e32 v147, v251, v229
	v_mul_f32_e32 v146, 0x3fb8aa3b, v146
	v_mul_f32_e32 v147, 0x3fb8aa3b, v147
	v_exp_f32_e32 v146, v146
	v_exp_f32_e32 v147, v147
	v_exp_f32_e32 v0, v0
	v_pk_mul_f32 v[144:145], v[144:145], v[146:147]
	v_sub_f32_e32 v146, v230, v229
	v_sub_f32_e32 v147, v231, v229
	v_mul_f32_e32 v146, 0x3fb8aa3b, v146
	v_mul_f32_e32 v147, 0x3fb8aa3b, v147
	v_exp_f32_e32 v146, v146
	v_exp_f32_e32 v147, v147
	v_pk_mul_f32 v[0:1], v[148:149], v[0:1]
	v_pk_mul_f32 v[146:147], v[130:131], v[146:147]
	v_sub_f32_e32 v130, v232, v229
	v_sub_f32_e32 v131, v233, v229
	v_mul_f32_e32 v130, 0x3fb8aa3b, v130
	v_mul_f32_e32 v131, 0x3fb8aa3b, v131
	v_exp_f32_e32 v130, v130
	v_exp_f32_e32 v131, v131
	v_cvt_pk_bf16_f32 v0, v0, v1
	v_cndmask_b32_e64 v1, v0, 0, s[18:19]
	v_lshrrev_b32_e32 v0, 16, v0
	v_pk_mul_f32 v[148:149], v[132:133], v[130:131]
	v_cvt_pk_bf16_f32 v130, v142, v143
	v_cvt_pk_bf16_f32 v131, v144, v145
	v_cvt_pk_bf16_f32 v132, v146, v147
	v_cvt_pk_bf16_f32 v133, v148, v149
	v_cndmask_b32_e64 v0, v0, 0, s[16:17]
	s_waitcnt lgkmcnt(0)
	s_nop 0
	v_mfma_f32_16x16x32_bf16 v[138:141], v[130:133], v[138:141], 0
	v_mfma_f32_16x16x32_bf16 v[134:137], v[130:133], v[134:137], 0
	v_mfma_f32_16x16x32_bf16 v[126:129], v[130:133], v[126:129], 0
	v_cvt_pk_bf16_f32 v130, v234, v235
	v_perm_b32 v131, v0, v1, s60
	v_mov_b32_e32 v132, v3
	v_mov_b32_e32 v133, v3
	s_nop 1
	v_mfma_f32_16x16x32_bf16 v[118:121], v[130:133], v[118:121], v[138:141]
	v_mfma_f32_16x16x32_bf16 v[114:117], v[130:133], v[114:117], v[134:137]
	v_mfma_f32_16x16x32_bf16 v[122:125], v[130:133], v[122:125], v[126:129]
